# v058 + NA wave->(row, head) map with wave bits 1,2 swapped so SIMD-sharing waves (w, w+4) hold query rows r and r+2 (active key-row steps overlap less)
# baseline (speedup 1.0000x reference)
; #define LAS __attribute__((address_space(3)))
; __device__ __forceinline__ void na_phase(LAS unsigned char* lds, const bf16_t* Q, const bf16_t* K, const bf16_t* V, bf16_t* Ob, const float* rpb, float negb) {
;     int tid_ = threadIdx.x; asm volatile("" : "+v"(tid_));
;     const int tid = tid_, lane = tid & 63, w = __builtin_amdgcn_readfirstlane(tid >> 6), l15 = lane & 15, g = lane >> 4;
;     LAS float* tab = (LAS float*)(lds + NA_TAB);
;     for (int it = 0;; ++it) {
;         const int item = item_of(it, NA_ITEMS_LAT, NA_ITEMS); if (item < 0) break;
;         const bool isctx = item >= NA_ITEMS_LAT;
;         int b, hp, rq;
;         if (!isctx) { b = item >> 8; hp = (item >> 5) & 7; rq = item & 31; } else { const int j = item - NA_ITEMS_LAT; b = j >> 3; hp = j & 7; rq = 0; }
;         const int hh = w >> 2, head = 2 * hp + hh;
;         const size_t ctx0 = (size_t)(MLAT + b * NCTX), lat0 = (size_t)(b * SEQ);
;         const int kr_lo = min(max(4 * rq - 4, 0), 120), kr_hi = min(max(4 * rq - 1, 0), 120) + 8;
;         const int NT = 4 + (isctx ? 0 : kr_hi - kr_lo);
;         const DmaLane dl = dma_lane(DM, hp * 128, w, lane);
;     ...
;         dma_tile<2>(lds, K, V, NA_ROW0(0), DM, dl, w);
;         dma_tile<2>(lds + NA_BUF, K, V, NA_ROW0(1), DM, dl, w);
;         dma_tile<2>(lds + 2 * NA_BUF, K, V, NA_ROW0(2), DM, dl, w);
;         for (int i = tid; i < 2 * 465; i += 512) { const int h2 = i / 465, e = i - h2 * 465; tab[h2 * 512 + e] = rpb[(2 * hp + h2) * 465 + e] * LOG2E; }
;         const int r = 4 * rq + (w & 3);
;         const size_t qrow0 = isctx ? (size_t)(MLAT + b * NCTX + (w & 3) * 64) : (size_t)(b * SEQ + r * 64);
;         bf16x8 qf[4][2];
; #pragma unroll
;         for (int grp = 0; grp < 4; ++grp)
; #pragma unroll
;             for (int ds = 0; ds < 2; ++ds) qf[grp][ds] = *(const bf16x8*)(Q + (qrow0 + 16 * grp + l15) * DM + head * 64 + 32 * ds + 8 * g);
;         f32x4 O[4][4]; float ls[4];
; #pragma unroll
;         for (int grp = 0; grp < 4; ++grp) { ls[grp] = 0.f;
; #pragma unroll
;             for (int db = 0; db < 4; ++db) O[grp][db] = (f32x4){0.f, 0.f, 0.f, 0.f}; }
;         const int r0w = min(max(r - 4, 0), 120);
.LBB0_359:
	s_and_b64 vcc, exec, s[0:1]
	s_cbranch_vccz .LBB0_450
	v_readlane_b32 s0, v241, 50
	v_readlane_b32 s1, v241, 51
	v_readlane_b32 s98, v240, 58
	v_readlane_b32 s99, v240, 59
	v_mov_b32_e32 v108, s98
	v_mov_b32_e32 v109, s99
	v_bfe_u32 v1, v152, 7, 1
	v_bfe_u32 v2, v152, 8, 1
	v_and_b32_e32 v198, 0x27f, v152
	v_lshl_or_b32 v198, v1, 8, v198
	v_lshl_or_b32 v198, v2, 7, v198
	v_mov_b32_e32 v111, v155
	s_mov_b32 s92, 0
	s_nop 0
	global_load_dword v0, v155, s[0:1]
	s_waitcnt vmcnt(0)
	v_xor_b32_e32 v0, 0x80000000, v0
	v_bfe_u32 v1, v198, 3, 3
	v_xor_b32_e32 v5, v1, v198
	v_and_b32_e32 v6, 1, v198
	v_bfe_u32 v7, v198, 3, 1
	v_bfe_u32 v4, v198, 4, 2
	v_and_b32_e32 v2, 7, v198
	v_bitop3_b32 v3, v1, v198, 7 bitop3:0x78
	v_and_or_b32 v5, v5, 6, v6
	v_and_or_b32 v8, v1, 2, v7
	v_readfirstlane_b32 s0, v198
	v_lshlrev_b32_e32 v201, 4, v3
	v_lshlrev_b32_e32 v202, 4, v5
	v_lshlrev_b32_e32 v154, 3, v4
	v_bitop3_b32 v3, v4, v198, 7 bitop3:0x78
	v_bitop3_b32 v2, v4, v2, 4 bitop3:0x36
	v_lshlrev_b32_e32 v5, 9, v4
	v_lshlrev_b32_e32 v206, 5, v8
	v_bfe_u32 v8, v198, 2, 2
	v_lshlrev_b32_e32 v4, 2, v4
	s_ashr_i32 s1, s0, 6
	v_and_b32_e32 v199, 15, v198
	s_ashr_i32 s6, s0, 8
	s_movk_i32 s0, 0x3a2
	v_or_b32_e32 v8, v4, v8
	v_cmp_gt_i32_e64 s[8:9], s0, v198
	v_lshlrev_b32_e32 v210, 7, v8
	v_sub_u32_e64 v8, v199, 8 clamp
	v_writelane_b32 v240, s8, 46
	s_and_b32 s2, s1, 3
	v_sub_u32_e32 v8, v4, v8
	v_lshlrev_b32_e32 v6, 11, v1
	v_writelane_b32 v240, s9, 47
	s_lshl_b32 s0, s2, 6
	v_add_u32_e32 v10, 1, v8
	v_lshl_or_b32 v200, s1, 14, v6
	s_lshl_b32 s63, s1, 10
	v_writelane_b32 v240, s0, 48
	v_readlane_b32 s0, v241, 37
	v_cmp_gt_u32_e64 s[10:11], 16, v10
	v_add_u32_e32 v10, 2, v8
	v_and_b32_e32 v110, 48, v198
	v_readlane_b32 s1, v241, 38
	v_cmp_gt_u32_e64 s[12:13], 16, v10
	v_add_u32_e32 v10, 3, v8
	v_lshl_add_u64 v[112:113], s[0:1], 0, v[110:111]
	s_lshl_b32 s0, s6, 13
	v_writelane_b32 v240, s6, 49
	s_lshl_b32 s1, s6, 11
	v_cmp_gt_u32_e64 s[14:15], 16, v10
	s_movk_i32 s6, 0xffef
	v_add_u32_e32 v10, 17, v8
	v_sub_u32_e32 v9, v4, v199
	v_cmp_gt_u32_e64 s[8:9], 16, v8
	v_cmp_lt_u32_e64 s[16:17], s6, v8
	v_cmp_gt_u32_e64 s[18:19], 16, v10
	v_add_u32_e32 v10, 18, v8
	v_add_u32_e32 v8, 19, v8
	v_cmp_gt_u32_e64 s[22:23], 16, v8
	v_add_u32_e32 v8, 1, v9
	v_cmp_gt_u32_e64 s[26:27], 16, v8
	v_add_u32_e32 v8, 2, v9
	v_cmp_gt_u32_e64 s[28:29], 16, v8
	v_add_u32_e32 v8, 3, v9
	v_cmp_gt_u32_e64 s[30:31], 16, v8
	v_add_u32_e32 v8, 17, v9
	v_cmp_gt_u32_e64 s[36:37], 16, v8
	v_add_u32_e32 v8, 18, v9
	v_cmp_gt_u32_e64 s[38:39], 16, v8
	v_add_u32_e32 v8, 19, v9
	v_cmp_gt_u32_e64 s[40:41], 16, v8
	v_and_or_b32 v8, v198, 63, 48
	v_cmp_gt_u32_e64 s[24:25], 16, v9
	v_cmp_lt_u32_e64 s[34:35], s6, v9
	v_add_u32_e32 v9, -8, v8
	v_min_u32_e32 v9, 48, v9
	v_sub_u32_e32 v4, v4, v9
	v_and_b32_e32 v9, -16, v4
	s_movk_i32 s6, 0xffe0
	v_cmp_gt_u32_e64 s[20:21], 16, v10
	v_cmp_eq_u32_e64 s[42:43], s6, v9
	v_add_u32_e32 v10, 33, v4
	s_movk_i32 s6, 0xffd0
	v_lshlrev_b32_e32 v204, 4, v2
	v_lshlrev_b32_e32 v2, 5, v198
	v_cmp_gt_u32_e64 s[44:45], 16, v10
	v_add_u32_e32 v10, 34, v4
	v_cmp_eq_u32_e64 s[50:51], s6, v9
	v_add_u32_e32 v9, 49, v4
	v_and_b32_e32 v6, 0x180, v2
	v_lshlrev_b32_e32 v2, 3, v198
	v_cmp_gt_u32_e64 s[46:47], 16, v10
	v_add_u32_e32 v10, 35, v4
	v_cmp_gt_u32_e64 s[52:53], 16, v9
	v_add_u32_e32 v9, 50, v4
	v_add_u32_e32 v4, 51, v4
	s_add_i32 s65, s0, 0
	v_lshlrev_b32_e32 v111, 7, v199
	v_and_b32_e32 v205, 24, v2
	v_cmp_gt_u32_e64 s[56:57], 16, v4
	v_readlane_b32 s6, v241, 43
	v_add_u32_e32 v4, s65, v5
	v_lshlrev_b32_e32 v203, 4, v3
	v_readlane_b32 s7, v241, 44
	v_add3_u32 v212, v4, v6, v205
	v_or_b32_e32 v4, s0, v111
	v_cmp_gt_u32_e64 s[54:55], 16, v9
	v_lshl_add_u64 v[114:115], s[6:7], 0, v[154:155]
	v_or_b32_e32 v9, v4, v204
	s_add_i32 s6, 0, 0x8000
	v_or_b32_e32 v4, v4, v203
	v_add_u32_e32 v214, s6, v4
	v_or3_b32 v4, s0, v5, v6
	v_lshlrev_b32_e32 v5, 2, v198
	v_and_or_b32 v5, v5, 64, v4
	v_lshlrev_b32_e32 v6, 5, v7
	v_xor_b32_e32 v209, 0x60, v206
	v_or3_b32 v5, v5, v6, v205
	v_xor_b32_e32 v207, 32, v206
	v_xor_b32_e32 v208, 64, v206
	v_add_u32_e32 v215, 0, v5
	v_or3_b32 v5, v4, v209, v205
	v_add_u32_e32 v216, 0, v5
	v_or3_b32 v5, v4, v208, v205
	v_or3_b32 v4, v4, v207, v205
	v_add_u32_e32 v218, 0, v4
	v_lshlrev_b32_e32 v4, 2, v8
	v_sub_u32_e32 v4, s1, v4
	v_add_u32_e32 v219, 0, v4
	v_lshlrev_b32_e32 v4, 2, v199
	v_sub_u32_e32 v4, s1, v4
	v_mov_b32_e32 v1, v0
	v_mov_b32_e32 v2, v0
	v_mov_b32_e32 v3, v0
	v_cmp_gt_u32_e64 s[48:49], 16, v10
	v_add_u32_e32 v211, s65, v111
	v_add_u32_e32 v213, s6, v9
	v_add_u32_e32 v217, 0, v5
	s_add_i32 s69, s63, 0
	v_add_u32_e32 v220, 0, v4
	s_branch .LBB0_362
